# v24 plus MLA final-tile PV first V-fragment group prefetched right after the last QK MFMA into a separate buffer
# speedup vs baseline: 1.0030x; 1.0030x over previous
.LBB0_571:
	v_readlane_b32 s10, v254, 61
	s_cmp_gt_i32 s7, s14
	s_mov_b32 s24, s10
	v_readlane_b32 s11, v254, 62
	s_cbranch_scc1 .LBB0_584
	s_add_i32 s3, 0, 0x10000
	v_lshl_add_u32 v108, v215, 7, s3
	s_or_b32 s3, s7, 63
	s_cmp_le_i32 s3, s6
	v_add_u32_e32 v180, v226, v225
	v_xad_u32 v181, v225, 32, v226
	v_xad_u32 v182, v225, 64, v226
	ds_read_b128 v[100:103], v180 offset:32768
	ds_read_b128 v[236:239], v180 offset:40960
	ds_read_b128 v[240:243], v181 offset:32768
	ds_read_b128 v[244:247], v181 offset:40960
	ds_read_b128 v[248:251], v182 offset:32768
	s_waitcnt lgkmcnt(4)
	v_mfma_f32_32x32x16_bf16 v[84:99], v[100:103], v[176:179], v[68:83]
	ds_read_b128 v[100:103], v182 offset:40960
	v_xad_u32 v183, v225, s26, v226
	s_waitcnt lgkmcnt(4)
	v_mfma_f32_32x32x16_bf16 v[68:83], v[236:239], v[176:179], v[68:83]
	ds_read_b128 v[236:239], v183 offset:32768
	s_waitcnt lgkmcnt(4)
	v_mfma_f32_32x32x16_bf16 v[84:99], v[240:243], v[172:175], v[84:99]
	ds_read_b128 v[240:243], v183 offset:40960
	v_xad_u32 v180, v225, s57, v226
	s_waitcnt lgkmcnt(4)
	v_mfma_f32_32x32x16_bf16 v[68:83], v[244:247], v[172:175], v[68:83]
	ds_read_b128 v[244:247], v180 offset:32768
	s_waitcnt lgkmcnt(4)
	v_mfma_f32_32x32x16_bf16 v[84:99], v[248:251], v[168:171], v[84:99]
	ds_read_b128 v[248:251], v180 offset:40960
	v_xad_u32 v181, v225, s90, v226
	s_waitcnt lgkmcnt(4)
	v_mfma_f32_32x32x16_bf16 v[68:83], v[100:103], v[168:171], v[68:83]
	ds_read_b128 v[100:103], v181 offset:32768
	s_waitcnt lgkmcnt(4)
	v_mfma_f32_32x32x16_bf16 v[84:99], v[236:239], v[164:167], v[84:99]
	ds_read_b128 v[236:239], v181 offset:40960
	v_xad_u32 v182, v225, s56, v226
	s_waitcnt lgkmcnt(4)
	v_mfma_f32_32x32x16_bf16 v[68:83], v[240:243], v[164:167], v[68:83]
	ds_read_b128 v[240:243], v182 offset:32768
	s_waitcnt lgkmcnt(4)
	v_mfma_f32_32x32x16_bf16 v[84:99], v[244:247], v[160:163], v[84:99]
	ds_read_b128 v[244:247], v182 offset:40960
	v_xad_u32 v183, v225, s74, v226
	s_waitcnt lgkmcnt(4)
	v_mfma_f32_32x32x16_bf16 v[68:83], v[248:251], v[160:163], v[68:83]
	ds_read_b128 v[248:251], v183 offset:32768
	s_waitcnt lgkmcnt(4)
	v_mfma_f32_32x32x16_bf16 v[84:99], v[100:103], v[156:159], v[84:99]
	ds_read_b128 v[100:103], v183 offset:40960
	v_xad_u32 v180, v2, v224, v108
	s_waitcnt lgkmcnt(4)
	v_mfma_f32_32x32x16_bf16 v[68:83], v[236:239], v[156:159], v[68:83]
	ds_read_b128 v[236:239], v180
	s_waitcnt lgkmcnt(4)
	v_mfma_f32_32x32x16_bf16 v[84:99], v[240:243], v[152:155], v[84:99]
	ds_read_b128 v[240:243], v180 offset:4096
	v_or_b32_e32 v184, 32, v2
	v_xad_u32 v181, v184, v224, v108
	s_waitcnt lgkmcnt(4)
	v_mfma_f32_32x32x16_bf16 v[68:83], v[244:247], v[152:155], v[68:83]
	ds_read_b128 v[244:247], v181
	s_waitcnt lgkmcnt(4)
	v_mfma_f32_32x32x16_bf16 v[84:99], v[248:251], v[148:151], v[84:99]
	ds_read_b128 v[248:251], v181 offset:4096
	v_or_b32_e32 v184, 64, v2
	v_xad_u32 v182, v184, v224, v108
	s_waitcnt lgkmcnt(4)
	v_mfma_f32_32x32x16_bf16 v[68:83], v[100:103], v[148:151], v[68:83]
	ds_read_b128 v[100:103], v182
	s_waitcnt lgkmcnt(4)
	v_mfma_f32_32x32x16_bf16 v[84:99], v[236:239], v[144:147], v[84:99]
	ds_read_b128 v[236:239], v182 offset:4096
	v_or_b32_e32 v184, 0x60, v2
	v_xad_u32 v183, v184, v224, v108
	s_waitcnt lgkmcnt(4)
	v_mfma_f32_32x32x16_bf16 v[68:83], v[240:243], v[144:147], v[68:83]
	ds_read_b128 v[240:243], v183
	s_waitcnt lgkmcnt(4)
	v_mfma_f32_32x32x16_bf16 v[84:99], v[244:247], v[140:143], v[84:99]
	ds_read_b128 v[244:247], v183 offset:4096
	s_waitcnt lgkmcnt(4)
	v_mfma_f32_32x32x16_bf16 v[68:83], v[248:251], v[140:143], v[68:83]
	s_waitcnt lgkmcnt(3)
	v_mfma_f32_32x32x16_bf16 v[84:99], v[100:103], v[136:139], v[84:99]
	s_waitcnt lgkmcnt(2)
	v_mfma_f32_32x32x16_bf16 v[68:83], v[236:239], v[136:139], v[68:83]
	s_waitcnt lgkmcnt(1)
	v_mfma_f32_32x32x16_bf16 v[84:99], v[240:243], v[132:135], v[84:99]
	s_waitcnt lgkmcnt(0)
	v_mfma_f32_32x32x16_bf16 v[68:83], v[244:247], v[132:135], v[68:83]
	ds_read_b64_tr_b16 v[236:237], v221 offset:0x0
	ds_read_b64_tr_b16 v[238:239], v221 offset:0x800
	ds_read_b64_tr_b16 v[240:241], v221 offset:0x1000
	ds_read_b64_tr_b16 v[242:243], v221 offset:0x1800
	ds_read_b64_tr_b16 v[244:245], v221 offset:0x2000
	ds_read_b64_tr_b16 v[246:247], v221 offset:0x2800
	ds_read_b64_tr_b16 v[248:249], v221 offset:0x3000
	ds_read_b64_tr_b16 v[250:251], v221 offset:0x3800
	s_nop 1
	s_cbranch_scc1 .LBB0_574
	v_sub_u32_e32 v2, v223, v216
	v_subrev_u32_e32 v2, s7, v2
	v_cmp_gt_u32_e32 vcc, 2.0, v2
	v_add_u32_e32 v100, 0xbfffffe0, v2
	s_nop 4
	v_cndmask_b32_e32 v84, v212, v84, vcc
	v_cmp_lt_u32_e32 vcc, s82, v100
	v_add_u32_e32 v100, 0xbfffffff, v2
	s_nop 0
	v_cndmask_b32_e32 v68, v212, v68, vcc
	v_cmp_lt_u32_e32 vcc, s82, v100
	v_add_u32_e32 v100, 0xbfffffdf, v2
	s_nop 0
	v_cndmask_b32_e32 v85, v212, v85, vcc
	v_cmp_lt_u32_e32 vcc, s82, v100
	v_add_u32_e32 v100, 0xbffffffe, v2
	s_nop 0
	v_cndmask_b32_e32 v69, v212, v69, vcc
	v_cmp_lt_u32_e32 vcc, s82, v100
	v_add_u32_e32 v100, 0xbfffffde, v2
	s_nop 0
	v_cndmask_b32_e32 v86, v212, v86, vcc
	v_cmp_lt_u32_e32 vcc, s82, v100
	v_add_u32_e32 v100, 0xbffffffd, v2
	s_nop 0
	v_cndmask_b32_e32 v70, v212, v70, vcc
	v_cmp_lt_u32_e32 vcc, s82, v100
	v_add_u32_e32 v100, 0xbfffffdd, v2
	s_nop 0
	v_cndmask_b32_e32 v87, v212, v87, vcc
	v_cmp_lt_u32_e32 vcc, s82, v100
	v_add_u32_e32 v100, 0xbffffff8, v2
	s_nop 0
	v_cndmask_b32_e32 v71, v212, v71, vcc
	v_cmp_lt_u32_e32 vcc, s82, v100
	v_add_u32_e32 v100, 0xbfffffd8, v2
	s_nop 0
	v_cndmask_b32_e32 v88, v212, v88, vcc
	v_cmp_lt_u32_e32 vcc, s82, v100
	v_add_u32_e32 v100, 0xbffffff7, v2
	s_nop 0
	v_cndmask_b32_e32 v72, v212, v72, vcc
	v_cmp_lt_u32_e32 vcc, s82, v100
	v_add_u32_e32 v100, 0xbfffffd7, v2
	s_nop 0
	v_cndmask_b32_e32 v89, v212, v89, vcc
	v_cmp_lt_u32_e32 vcc, s82, v100
	v_add_u32_e32 v100, 0xbffffff6, v2
	s_nop 0
	v_cndmask_b32_e32 v73, v212, v73, vcc
	v_cmp_lt_u32_e32 vcc, s82, v100
	v_add_u32_e32 v100, 0xbfffffd6, v2
	s_nop 0
	v_cndmask_b32_e32 v90, v212, v90, vcc
	v_cmp_lt_u32_e32 vcc, s82, v100
	v_add_u32_e32 v100, 0xbffffff5, v2
	s_nop 0
	v_cndmask_b32_e32 v74, v212, v74, vcc
	v_cmp_lt_u32_e32 vcc, s82, v100
	v_add_u32_e32 v100, 0xbfffffd5, v2
	s_nop 0
	v_cndmask_b32_e32 v91, v212, v91, vcc
	v_cmp_lt_u32_e32 vcc, s82, v100
	v_add_u32_e32 v100, 0xbffffff0, v2
	s_nop 0
	v_cndmask_b32_e32 v75, v212, v75, vcc
	v_cmp_lt_u32_e32 vcc, s82, v100
	v_add_u32_e32 v100, 0xbfffffd0, v2
	s_nop 0
	v_cndmask_b32_e32 v92, v212, v92, vcc
	v_cmp_lt_u32_e32 vcc, s82, v100
	v_add_u32_e32 v100, 0xbfffffef, v2
	s_nop 0
	v_cndmask_b32_e32 v76, v212, v76, vcc
	v_cmp_lt_u32_e32 vcc, s82, v100
	v_add_u32_e32 v100, 0xbfffffcf, v2
	s_nop 0
	v_cndmask_b32_e32 v93, v212, v93, vcc
	v_cmp_lt_u32_e32 vcc, s82, v100
	v_add_u32_e32 v100, 0xbfffffee, v2
	s_nop 0
	v_cndmask_b32_e32 v77, v212, v77, vcc
	v_cmp_lt_u32_e32 vcc, s82, v100
	v_add_u32_e32 v100, 0xbfffffce, v2
	s_nop 0
	v_cndmask_b32_e32 v94, v212, v94, vcc
	v_cmp_lt_u32_e32 vcc, s82, v100
	v_add_u32_e32 v100, 0xbfffffed, v2
	s_nop 0
	v_cndmask_b32_e32 v78, v212, v78, vcc
	v_cmp_lt_u32_e32 vcc, s82, v100
	v_add_u32_e32 v100, 0xbfffffcd, v2
	s_nop 0
	v_cndmask_b32_e32 v95, v212, v95, vcc
	v_cmp_lt_u32_e32 vcc, s82, v100
	v_add_u32_e32 v100, 0xbfffffe8, v2
	s_nop 0
	v_cndmask_b32_e32 v79, v212, v79, vcc
	v_cmp_lt_u32_e32 vcc, s82, v100
	v_add_u32_e32 v100, 0xbfffffc8, v2
	s_nop 0
	v_cndmask_b32_e32 v96, v212, v96, vcc
	v_cmp_lt_u32_e32 vcc, s82, v100
	v_add_u32_e32 v100, 0xbfffffe7, v2
	s_nop 0
	v_cndmask_b32_e32 v80, v212, v80, vcc
	v_cmp_lt_u32_e32 vcc, s82, v100
	v_add_u32_e32 v100, 0xbfffffc7, v2
	s_nop 0
	v_cndmask_b32_e32 v97, v212, v97, vcc
	v_cmp_lt_u32_e32 vcc, s82, v100
	v_add_u32_e32 v100, 0xbfffffe6, v2
	s_nop 0
	v_cndmask_b32_e32 v81, v212, v81, vcc
	v_cmp_lt_u32_e32 vcc, s82, v100
	v_add_u32_e32 v100, 0xbfffffc6, v2
	s_nop 0
	v_cndmask_b32_e32 v98, v212, v98, vcc
	v_cmp_lt_u32_e32 vcc, s82, v100
	v_add_u32_e32 v100, 0xbfffffe5, v2
	v_add_u32_e32 v2, 0xbfffffc5, v2
	v_cndmask_b32_e32 v82, v212, v82, vcc
	v_cmp_lt_u32_e32 vcc, s82, v100
	s_nop 1
	v_cndmask_b32_e32 v99, v212, v99, vcc
	v_cmp_lt_u32_e32 vcc, s82, v2
	s_nop 1
	v_cndmask_b32_e32 v83, v212, v83, vcc

.LBB0_583:
	v_add_f32_e32 v100, v84, v85
	v_fmac_f32_e32 v100, v222, v2
	s_waitcnt lgkmcnt(6)
	s_nop 0
	v_mfma_f32_32x32x16_bf16 v[4:19], v[68:71], v[236:239], v[4:19]
	ds_read_b64_tr_b16 v[84:85], v221 offset:0x200
	ds_read_b64_tr_b16 v[86:87], v221 offset:0xa00
	s_waitcnt lgkmcnt(6)
	v_mfma_f32_32x32x16_bf16 v[4:19], v[72:75], v[240:243], v[4:19]
	ds_read_b64_tr_b16 v[88:89], v221 offset:0x1200
	ds_read_b64_tr_b16 v[90:91], v221 offset:0x1a00
	s_waitcnt lgkmcnt(6)
	v_mfma_f32_32x32x16_bf16 v[4:19], v[76:79], v[244:247], v[4:19]
	ds_read_b64_tr_b16 v[92:93], v221 offset:0x2200
	ds_read_b64_tr_b16 v[94:95], v221 offset:0x2a00
	s_waitcnt lgkmcnt(6)
	v_mfma_f32_32x32x16_bf16 v[4:19], v[80:83], v[248:251], v[4:19]
	ds_read_b64_tr_b16 v[96:97], v221 offset:0x3200
	ds_read_b64_tr_b16 v[98:99], v221 offset:0x3a00
	s_waitcnt lgkmcnt(6)
	v_mfma_f32_32x32x16_bf16 v[52:67], v[68:71], v[84:87], v[52:67]
	ds_read_b64_tr_b16 v[84:85], v221 offset:0x400
	ds_read_b64_tr_b16 v[86:87], v221 offset:0xc00
	s_waitcnt lgkmcnt(6)
	v_mfma_f32_32x32x16_bf16 v[52:67], v[72:75], v[88:91], v[52:67]
	ds_read_b64_tr_b16 v[88:89], v221 offset:0x1400
	ds_read_b64_tr_b16 v[90:91], v221 offset:0x1c00
	s_waitcnt lgkmcnt(6)
	v_mfma_f32_32x32x16_bf16 v[52:67], v[76:79], v[92:95], v[52:67]
	ds_read_b64_tr_b16 v[92:93], v221 offset:0x2400
	ds_read_b64_tr_b16 v[94:95], v221 offset:0x2c00
	s_waitcnt lgkmcnt(6)
	v_mfma_f32_32x32x16_bf16 v[52:67], v[80:83], v[96:99], v[52:67]
	ds_read_b64_tr_b16 v[96:97], v221 offset:0x3400
	ds_read_b64_tr_b16 v[98:99], v221 offset:0x3c00
	s_waitcnt lgkmcnt(6)
	v_mfma_f32_32x32x16_bf16 v[20:35], v[68:71], v[84:87], v[20:35]
	ds_read_b64_tr_b16 v[84:85], v221 offset:0x600
	ds_read_b64_tr_b16 v[86:87], v221 offset:0xe00
	s_waitcnt lgkmcnt(6)
	v_mfma_f32_32x32x16_bf16 v[20:35], v[72:75], v[88:91], v[20:35]
	ds_read_b64_tr_b16 v[88:89], v221 offset:0x1600
	ds_read_b64_tr_b16 v[90:91], v221 offset:0x1e00
	s_waitcnt lgkmcnt(6)
	v_mfma_f32_32x32x16_bf16 v[20:35], v[76:79], v[92:95], v[20:35]
	ds_read_b64_tr_b16 v[92:93], v221 offset:0x2600
	ds_read_b64_tr_b16 v[94:95], v221 offset:0x2e00
	s_waitcnt lgkmcnt(6)
	v_mfma_f32_32x32x16_bf16 v[20:35], v[80:83], v[96:99], v[20:35]
	ds_read_b64_tr_b16 v[96:97], v221 offset:0x3600
	ds_read_b64_tr_b16 v[98:99], v221 offset:0x3e00
	s_waitcnt lgkmcnt(6)
	v_mfma_f32_32x32x16_bf16 v[36:51], v[68:71], v[84:87], v[36:51]
	v_mov_b32_e32 v222, v100
	s_waitcnt lgkmcnt(4)
	v_mfma_f32_32x32x16_bf16 v[36:51], v[72:75], v[88:91], v[36:51]
	s_waitcnt lgkmcnt(2)
	v_mfma_f32_32x32x16_bf16 v[36:51], v[76:79], v[92:95], v[36:51]
	s_waitcnt lgkmcnt(0)
	v_mfma_f32_32x32x16_bf16 v[36:51], v[80:83], v[96:99], v[36:51]
